# SWA local tiles: dropped the second (post-exp) key mask select - masked scores are -1e30 before the max so exp2 already returns exactly 0
# baseline (speedup 1.0000x reference)
; #define LAS __attribute__((address_space(3)))
; template <bool SWA>
; DI void attn_phase(const Ctx& a, LAS unsigned char* lds) {
;     ...
;                 float sv[16]; bool ok[16];
; #pragma unroll
;                 for (int jt = 0; jt < 4; ++jt)
; #pragma unroll
;                     for (int rr = 0; rr < 4; ++rr) {
;                         bool valid = true;
;                         if (SWA && local) { const int dd = tkey0 + 16 * jt + 4 * fq + rr - (tq0 + fr); valid = (dd <= 128) && (dd >= -128); }
;                         sv[jt * 4 + rr] = valid ? sc[jt][rr] : -1e30f; ok[jt * 4 + rr] = valid;
;                     }
;                 float cmax = sv[0];
; #pragma unroll
;                 for (int e = 1; e < 16; ++e) cmax = fmaxf(cmax, sv[e]);
;                 cmax = fmaxf(cmax, shx(cmax, 16, lane)); cmax = fmaxf(cmax, shx(cmax, 32, lane));
;                 const float m_new = fmaxf(m_run, cmax);
;                 const float alpha = __builtin_amdgcn_exp2f((m_run - m_new) * LOG2E);
;                 float p[16], psum = 0.f;
; #pragma unroll
;                 for (int e = 0; e < 16; ++e) { p[e] = ok[e] ? __builtin_amdgcn_exp2f((sv[e] - m_new) * LOG2E) : 0.f; psum += p[e]; }
;                 l_run = l_run * alpha + psum; m_run = m_new;
;                 u32x4 pw0, pw1; pw0.x = pk2(p[0], p[1]); pw0.y = pk2(p[2], p[3]); pw0.z = pk2(p[4], p[5]); pw0.w = pk2(p[6], p[7]);
;                 pw1.x = pk2(p[8], p[9]); pw1.y = pk2(p[10], p[11]); pw1.z = pk2(p[12], p[13]); pw1.w = pk2(p[14], p[15]);
;                 const bf16x8 pf0 = __builtin_bit_cast(bf16x8, pw0), pf1 = __builtin_bit_cast(bf16x8, pw1);
;                 if (__builtin_amdgcn_ballot_w64(alpha != 1.f) != 0ull) {
; #pragma unroll
;                     for (int dt = 0; dt < 4; ++dt) o[dt] = o[dt] * alpha;
;                 }
;                 const int kc = (fq >> 1), kb8 = (fq & 1) * 8;
; #pragma unroll
;                 for (int dt = 0; dt < 4; ++dt) {
;                     const int d = 16 * dt + fr, sw = (d >> 1) & 7; const int vb = AT_V + buf * 8192 + d * 128 + kb8;
;                     const s16x4 v0 = *(const LAS s16x4*)(lds + vb + ((kc ^ sw) << 4)), v1 = *(const LAS s16x4*)(lds + vb + (((kc + 2) ^ sw) << 4));
;                     const s16x4 v2 = *(const LAS s16x4*)(lds + vb + (((kc + 4) ^ sw) << 4)), v3 = *(const LAS s16x4*)(lds + vb + (((kc + 6) ^ sw) << 4));
.LBB0_115:
	v_add_u32_e32 v77, s79, v74
	v_add_u32_e32 v106, v77, v70
	v_add_u32_e32 v107, v77, v71
	ds_read_b64 v[116:117], v106 offset:24576
	ds_read_b64 v[118:119], v107 offset:24576
	ds_read_b64 v[120:121], v106 offset:26624
	ds_read_b64 v[122:123], v107 offset:26624
	s_mov_b32 s98, 0x3fb8aa3b
	v_mul_f32_e32 v190, 0xbfb8aa3b, v28
	v_fma_f32 v29, v29, s98, v190
	v_fma_f32 v30, v30, s98, v190
	v_fma_f32 v31, v31, s98, v190
	v_fma_f32 v32, v32, s98, v190
	v_fma_f32 v33, v33, s98, v190
	v_fma_f32 v34, v34, s98, v190
	v_fma_f32 v35, v35, s98, v190
	v_fma_f32 v36, v36, s98, v190
	v_exp_f32_e32 v29, v29
	v_exp_f32_e32 v30, v30
	v_exp_f32_e32 v31, v31
	v_exp_f32_e32 v32, v32
	v_exp_f32_e32 v33, v33
	v_exp_f32_e32 v34, v34
	v_exp_f32_e32 v35, v35
	v_exp_f32_e32 v36, v36
	v_add_u32_e32 v108, v77, v72
	v_add_u32_e32 v77, v77, v73
	ds_read_b64 v[124:125], v108 offset:24576
	ds_read_b64 v[126:127], v77 offset:24576
	ds_read_b64 v[128:129], v108 offset:26624
	ds_read_b64 v[130:131], v77 offset:26624
	s_waitcnt lgkmcnt(0)
	ds_read_b64 v[132:133], v106 offset:28672
	ds_read_b64 v[134:135], v107 offset:28672
	ds_read_b64 v[136:137], v106 offset:30720
	ds_read_b64 v[138:139], v107 offset:30720
	ds_read_b64 v[140:141], v108 offset:28672
	ds_read_b64 v[142:143], v77 offset:28672
	ds_read_b64 v[160:161], v108 offset:30720
	ds_read_b64 v[162:163], v77 offset:30720
	v_fma_f32 v37, v37, s98, v190
	v_fma_f32 v38, v38, s98, v190
	v_fma_f32 v39, v39, s98, v190
	v_fma_f32 v49, v49, s98, v190
	v_fma_f32 v51, v51, s98, v190
	v_fma_f32 v55, v55, s98, v190
	v_fma_f32 v60, v60, s98, v190
	v_fma_f32 v76, v76, s98, v190
	v_exp_f32_e32 v37, v37
	v_exp_f32_e32 v38, v38
	v_exp_f32_e32 v39, v39
	v_exp_f32_e32 v49, v49
	v_exp_f32_e32 v51, v51
	v_exp_f32_e32 v55, v55
	v_exp_f32_e32 v60, v60
	v_exp_f32_e32 v76, v76
	v_cvt_pk_bf16_f32 v78, v29, v30
	v_cvt_pk_bf16_f32 v79, v31, v32
	v_cvt_pk_bf16_f32 v80, v33, v34
	v_cvt_pk_bf16_f32 v81, v35, v36
	s_nop 1
	v_mfma_f32_16x16x32_bf16 v[20:23], v[116:119], v[78:81], v[20:23]
	s_nop 0
	v_mfma_f32_16x16x32_bf16 v[8:11], v[120:123], v[78:81], v[8:11]
	v_cvt_pk_bf16_f32 v82, v37, v38
	v_cvt_pk_bf16_f32 v83, v39, v49
	v_cvt_pk_bf16_f32 v84, v51, v55
	v_cvt_pk_bf16_f32 v85, v60, v76
	s_mov_b64 s[40:41], -1
	s_and_b64 vcc, exec, s[30:31]
	v_mfma_f32_16x16x32_bf16 v[8:11], v[128:131], v[82:85], v[8:11]
	v_mfma_f32_16x16x32_bf16 v[20:23], v[124:127], v[82:85], v[20:23]
	s_waitcnt lgkmcnt(0)
	v_mfma_f32_16x16x32_bf16 v[4:7], v[132:135], v[78:81], v[4:7]
	v_mfma_f32_16x16x32_bf16 v[0:3], v[136:139], v[78:81], v[0:3]
	v_mfma_f32_16x16x32_bf16 v[4:7], v[140:143], v[82:85], v[4:7]
	v_mfma_f32_16x16x32_bf16 v[0:3], v[160:163], v[82:85], v[0:3]
	s_cbranch_vccz .LBB0_117
	s_waitcnt vmcnt(0)
	s_mov_b64 s[40:41], 0
